# phase 0 weight transpose (w_in, w_kv): per-element load-scale-wait-multiply chains replaced by batched scale loads + multiplies at the tile loop top
# speedup vs baseline: 1.0292x; 1.0292x over previous
.LBB0_72:
	s_mov_b64 s[2:3], s[0:1]
	s_load_dwordx4 s[20:23], s[2:3], 0x0
	s_load_dwordx2 s[46:47], s[2:3], 0x10
	s_load_dwordx4 s[28:31], s[2:3], 0x48
	s_load_dwordx4 s[24:27], s[2:3], 0xd8
	s_load_dwordx4 s[36:39], s[2:3], 0xa0
	s_load_dwordx8 s[12:19], s[2:3], 0x80
	v_mov_b32_e32 v8, v156
	s_mov_b32 s2, s94
	v_mov_b32_e32 v16, v156
	s_cmpk_gt_i32 s2, 0x77f
	s_cbranch_scc1 .LBB0_108
	s_ashr_i32 s3, s2, 31
	s_lshr_b32 s3, s3, 28
	s_add_i32 s4, s2, s3
	s_and_b32 s3, s4, 0x3fffff0
	s_lshl_b32 s4, s4, 2
	s_sub_i32 s3, s2, s3
	s_andn2_b32 s4, s4, 63
	s_lshl_b32 s3, s3, 6
	s_or_b32 s5, s4, 8
	s_cmpk_lt_i32 s2, 0x400
	s_cselect_b32 s4, s4, s5
	s_ashr_i32 s5, s4, 31
	s_lshl_b64 s[4:5], s[4:5], 2
	v_and_b32_e32 v0, 63, v16
	s_waitcnt lgkmcnt(0)
	s_add_u32 s4, s30, s4
	v_mov_b32_e32 v11, 0
	s_addc_u32 s5, s31, s5
	v_lshlrev_b32_e32 v10, 2, v0
	v_ashrrev_i32_e32 v17, 6, v16
	v_lshl_add_u64 v[12:13], s[4:5], 0, v[10:11]
	v_add_u32_e32 v2, s3, v17
	s_movk_i32 s4, 0x7820
	v_mad_i64_i32 v[0:1], s[6:7], v2, s4, v[12:13]
	s_mov_b32 s100, 0
	global_load_dword v0, v[0:1], off
	s_cmp_lg_u64 s[28:29], 0
	s_cselect_b64 s[6:7], -1, 0
	s_cmp_eq_u64 s[28:29], 0
	s_cbranch_scc1 .LBB0_75
	v_ashrrev_i32_e32 v3, 31, v2
	v_lshl_add_u64 v[2:3], v[2:3], 2, s[28:29]
	global_load_dword v200, v[2:3], off
.LBB0_75:
	v_add_u32_e32 v1, 0x200, v16
	v_ashrrev_i32_e32 v25, 6, v1
	v_add_u32_e32 v2, s3, v25
	v_mad_i64_i32 v[4:5], s[4:5], v2, s4, v[12:13]
	global_load_dword v1, v[4:5], off
	v_cndmask_b32_e64 v3, 0, 1, s[6:7]
	v_cmp_ne_u32_e64 s[4:5], 1, v3
	s_andn2_b64 vcc, exec, s[6:7]
	s_cbranch_vccnz .LBB0_77
	v_ashrrev_i32_e32 v3, 31, v2
	v_lshl_add_u64 v[2:3], v[2:3], 2, s[28:29]
	global_load_dword v201, v[2:3], off
.LBB0_77:
	v_add_u32_e32 v2, 0x400, v16
	v_ashrrev_i32_e32 v24, 6, v2
	v_add_u32_e32 v4, s3, v24
	s_movk_i32 s6, 0x7820
	v_mad_i64_i32 v[2:3], s[8:9], v4, s6, v[12:13]
	global_load_dword v2, v[2:3], off
	s_and_b64 vcc, exec, s[4:5]
	s_cbranch_vccnz .LBB0_79
	v_ashrrev_i32_e32 v5, 31, v4
	v_lshl_add_u64 v[4:5], v[4:5], 2, s[28:29]
	global_load_dword v202, v[4:5], off
.LBB0_79:
	v_add_u32_e32 v3, 0x600, v16
	v_ashrrev_i32_e32 v23, 6, v3
	v_add_u32_e32 v4, s3, v23
	v_mad_i64_i32 v[6:7], s[6:7], v4, s6, v[12:13]
	global_load_dword v3, v[6:7], off
	s_and_b64 vcc, exec, s[4:5]
	s_cbranch_vccnz .LBB0_81
	v_ashrrev_i32_e32 v5, 31, v4
	v_lshl_add_u64 v[4:5], v[4:5], 2, s[28:29]
	global_load_dword v203, v[4:5], off
.LBB0_81:
	v_add_u32_e32 v4, 0x800, v16
	v_ashrrev_i32_e32 v22, 6, v4
	v_add_u32_e32 v6, s3, v22
	s_movk_i32 s6, 0x7820
	v_mad_i64_i32 v[4:5], s[8:9], v6, s6, v[12:13]
	global_load_dword v4, v[4:5], off
	s_and_b64 vcc, exec, s[4:5]
	s_cbranch_vccnz .LBB0_83
	v_ashrrev_i32_e32 v7, 31, v6
	v_lshl_add_u64 v[6:7], v[6:7], 2, s[28:29]
	global_load_dword v204, v[6:7], off
.LBB0_83:
	v_add_u32_e32 v5, 0xa00, v16
	v_ashrrev_i32_e32 v21, 6, v5
	v_add_u32_e32 v6, s3, v21
	v_mad_i64_i32 v[14:15], s[6:7], v6, s6, v[12:13]
	global_load_dword v5, v[14:15], off
	s_and_b64 vcc, exec, s[4:5]
	s_cbranch_vccnz .LBB0_85
	v_ashrrev_i32_e32 v7, 31, v6
	v_lshl_add_u64 v[6:7], v[6:7], 2, s[28:29]
	global_load_dword v205, v[6:7], off
.LBB0_85:
	v_add_u32_e32 v6, 0xc00, v16
	v_ashrrev_i32_e32 v20, 6, v6
	v_add_u32_e32 v14, s3, v20
	s_movk_i32 s6, 0x7820
	v_mad_i64_i32 v[6:7], s[8:9], v14, s6, v[12:13]
	global_load_dword v6, v[6:7], off
	s_and_b64 vcc, exec, s[4:5]
	s_cbranch_vccnz .LBB0_87
	v_ashrrev_i32_e32 v15, 31, v14
	v_lshl_add_u64 v[14:15], v[14:15], 2, s[28:29]
	global_load_dword v206, v[14:15], off
.LBB0_87:
	v_add_u32_e32 v7, 0xe00, v16
	v_ashrrev_i32_e32 v19, 6, v7
	v_add_u32_e32 v14, s3, v19
	v_mad_i64_i32 v[12:13], s[6:7], v14, s6, v[12:13]
	global_load_dword v7, v[12:13], off
	s_and_b64 vcc, exec, s[4:5]
	s_cbranch_vccnz .LBB0_89
	v_ashrrev_i32_e32 v15, 31, v14
	v_lshl_add_u64 v[12:13], v[14:15], 2, s[28:29]
	global_load_dword v207, v[12:13], off
	s_mov_b32 s100, 1

.LBB0_91:
	s_add_i32 s33, s42, s34
	s_cmpk_gt_i32 s33, 0x77f
	s_cselect_b64 s[6:7], -1, 0
	s_and_b64 vcc, exec, s[6:7]
	s_waitcnt vmcnt(0)
	s_cmp_eq_u32 s100, 0
	s_cbranch_scc1 .Lp0nm_0
	v_mul_f32_e32 v0, v0, v200
	v_mul_f32_e32 v1, v1, v201
	v_mul_f32_e32 v2, v2, v202
	v_mul_f32_e32 v3, v3, v203
	v_mul_f32_e32 v4, v4, v204
	v_mul_f32_e32 v5, v5, v205
	v_mul_f32_e32 v6, v6, v206
	v_mul_f32_e32 v7, v7, v207
.Lp0nm_0:
	ds_write_b32 v27, v0
	s_waitcnt vmcnt(6)
	ds_write_b32 v28, v1
	s_waitcnt vmcnt(5)
	ds_write_b32 v29, v2
	s_waitcnt vmcnt(4)
	ds_write_b32 v30, v3
	s_waitcnt vmcnt(3)
	ds_write_b32 v31, v4
	s_waitcnt vmcnt(2)
	ds_write_b32 v32, v5
	s_waitcnt vmcnt(1)
	ds_write_b32 v33, v6
	s_waitcnt vmcnt(0)
	ds_write_b32 v34, v7
	s_waitcnt lgkmcnt(0)
	s_barrier
	s_cbranch_vccnz .LBB0_90
	s_ashr_i32 s43, s33, 31
	s_lshr_b32 s43, s43, 28
	s_add_i32 s43, s33, s43
	s_ashr_i32 s43, s43, 4
	s_lshl_b32 s48, s43, 6
	s_or_b32 s49, s48, 8
	s_cmpk_lt_i32 s33, 0x400
	s_cselect_b32 s48, s48, s49
	s_ashr_i32 s49, s48, 31
	s_lshl_b32 s43, s43, 10
	v_lshl_add_u64 v[14:15], s[48:49], 2, v[12:13]
	s_sub_i32 s48, s3, s43
	v_add_u32_e32 v2, s48, v26
	v_mad_i64_i32 v[0:1], s[48:49], v2, s9, v[14:15]
	s_mov_b32 s100, 0
	global_load_dword v0, v[0:1], off
	s_and_b64 vcc, exec, s[4:5]
	s_cbranch_vccnz .LBB0_94
	v_ashrrev_i32_e32 v3, 31, v2
	v_lshl_add_u64 v[2:3], v[2:3], 2, s[28:29]
	global_load_dword v200, v[2:3], off
.LBB0_94:
	s_sub_i32 s43, 0, s43
	s_add_i32 s43, s43, s3
	v_add_u32_e32 v2, s43, v25
	v_mad_i64_i32 v[4:5], s[48:49], v2, s9, v[14:15]
	global_load_dword v1, v[4:5], off
	s_and_b64 vcc, exec, s[4:5]
	s_cbranch_vccnz .LBB0_96
	v_ashrrev_i32_e32 v3, 31, v2
	v_lshl_add_u64 v[2:3], v[2:3], 2, s[28:29]
	global_load_dword v201, v[2:3], off
.LBB0_96:
	v_add_u32_e32 v4, s43, v24
	v_mad_i64_i32 v[2:3], s[48:49], v4, s9, v[14:15]
	global_load_dword v2, v[2:3], off
	s_and_b64 vcc, exec, s[4:5]
	s_cbranch_vccnz .LBB0_98
	v_ashrrev_i32_e32 v5, 31, v4
	v_lshl_add_u64 v[4:5], v[4:5], 2, s[28:29]
	global_load_dword v202, v[4:5], off
.LBB0_98:
	v_add_u32_e32 v4, s43, v23
	v_mad_i64_i32 v[6:7], s[48:49], v4, s9, v[14:15]
	global_load_dword v3, v[6:7], off
	s_and_b64 vcc, exec, s[4:5]
	s_cbranch_vccnz .LBB0_100
	v_ashrrev_i32_e32 v5, 31, v4
	v_lshl_add_u64 v[4:5], v[4:5], 2, s[28:29]
	global_load_dword v203, v[4:5], off
.LBB0_100:
	v_add_u32_e32 v6, s43, v22
	v_mad_i64_i32 v[4:5], s[48:49], v6, s9, v[14:15]
	global_load_dword v4, v[4:5], off
	s_and_b64 vcc, exec, s[4:5]
	s_cbranch_vccnz .LBB0_102
	v_ashrrev_i32_e32 v7, 31, v6
	v_lshl_add_u64 v[6:7], v[6:7], 2, s[28:29]
	global_load_dword v204, v[6:7], off
.LBB0_102:
	v_add_u32_e32 v6, s43, v21
	v_mad_i64_i32 v[16:17], s[48:49], v6, s9, v[14:15]
	global_load_dword v5, v[16:17], off
	s_and_b64 vcc, exec, s[4:5]
	s_cbranch_vccnz .LBB0_104
	v_ashrrev_i32_e32 v7, 31, v6
	v_lshl_add_u64 v[6:7], v[6:7], 2, s[28:29]
	global_load_dword v205, v[6:7], off
.LBB0_104:
	v_add_u32_e32 v16, s43, v20
	v_mad_i64_i32 v[6:7], s[48:49], v16, s9, v[14:15]
	global_load_dword v6, v[6:7], off
	s_and_b64 vcc, exec, s[4:5]
	s_cbranch_vccnz .LBB0_106
	v_ashrrev_i32_e32 v17, 31, v16
	v_lshl_add_u64 v[16:17], v[16:17], 2, s[28:29]
	global_load_dword v206, v[16:17], off
.LBB0_106:
	v_add_u32_e32 v16, s43, v19
	v_mad_i64_i32 v[14:15], s[48:49], v16, s9, v[14:15]
	global_load_dword v7, v[14:15], off
	s_and_b64 vcc, exec, s[4:5]
	s_cbranch_vccnz .LBB0_90
	v_ashrrev_i32_e32 v17, 31, v16
	v_lshl_add_u64 v[14:15], v[16:17], 2, s[28:29]
	global_load_dword v207, v[14:15], off
	s_mov_b32 s100, 1
	s_branch .LBB0_90
.LBB0_108:
	s_cmpk_lt_i32 s2, 0x100
	v_mov_b32_e32 v16, v156
	s_cselect_b64 s[6:7], -1, 0
	s_cmpk_gt_i32 s2, 0xff
	s_cbranch_scc1 .LBB0_144
	s_ashr_i32 s3, s2, 31
	s_lshr_b32 s3, s3, 28
	s_add_i32 s4, s2, s3
	s_and_b32 s3, s4, 0x3fffff0
	s_lshl_b32 s4, s4, 2
	s_andn2_b32 s4, s4, 63
	s_sub_i32 s3, s2, s3
	s_ashr_i32 s5, s4, 31
	s_lshl_b32 s3, s3, 6
	s_lshl_b64 s[4:5], s[4:5], 2
	v_ashrrev_i32_e32 v17, 6, v16
	s_waitcnt vmcnt(8)
	v_and_b32_e32 v0, 63, v16
	s_waitcnt lgkmcnt(0)
	s_add_u32 s4, s14, s4
	s_waitcnt vmcnt(6)
	v_add_u32_e32 v2, s3, v17
	v_mov_b32_e32 v11, 0
	s_addc_u32 s5, s15, s5
	v_lshlrev_b32_e32 v10, 2, v0
	s_waitcnt vmcnt(5)
	v_ashrrev_i32_e32 v3, 31, v2
	v_lshl_add_u64 v[12:13], s[4:5], 0, v[10:11]
	v_lshlrev_b64 v[0:1], 12, v[2:3]
	v_lshl_add_u64 v[0:1], v[12:13], 0, v[0:1]
	s_mov_b32 s100, 0
	global_load_dword v0, v[0:1], off
	s_cmp_lg_u64 s[12:13], 0
	s_cselect_b64 s[8:9], -1, 0
	s_cmp_eq_u64 s[12:13], 0
	s_cbranch_scc1 .LBB0_111
	v_lshl_add_u64 v[2:3], v[2:3], 2, s[12:13]
	global_load_dword v200, v[2:3], off
.LBB0_111:
	v_add_u32_e32 v1, 0x200, v16
	v_ashrrev_i32_e32 v25, 6, v1
	v_add_u32_e32 v2, s3, v25
	v_ashrrev_i32_e32 v3, 31, v2
	s_waitcnt vmcnt(4)
	v_lshlrev_b64 v[4:5], 12, v[2:3]
	v_lshl_add_u64 v[4:5], v[12:13], 0, v[4:5]
	global_load_dword v1, v[4:5], off
	v_cndmask_b32_e64 v4, 0, 1, s[8:9]
	v_cmp_ne_u32_e64 s[4:5], 1, v4
	s_andn2_b64 vcc, exec, s[8:9]
	s_cbranch_vccnz .LBB0_113
	v_lshl_add_u64 v[2:3], v[2:3], 2, s[12:13]
	global_load_dword v201, v[2:3], off
.LBB0_113:
	v_add_u32_e32 v2, 0x400, v16
	v_ashrrev_i32_e32 v24, 6, v2
	v_add_u32_e32 v4, s3, v24
	v_ashrrev_i32_e32 v5, 31, v4
	v_lshlrev_b64 v[2:3], 12, v[4:5]
	v_lshl_add_u64 v[2:3], v[12:13], 0, v[2:3]
	global_load_dword v2, v[2:3], off
	s_and_b64 vcc, exec, s[4:5]
	s_cbranch_vccnz .LBB0_115
	v_lshl_add_u64 v[4:5], v[4:5], 2, s[12:13]
	global_load_dword v202, v[4:5], off
.LBB0_115:
	v_add_u32_e32 v3, 0x600, v16
	v_ashrrev_i32_e32 v23, 6, v3
	v_add_u32_e32 v4, s3, v23
	v_ashrrev_i32_e32 v5, 31, v4
	s_waitcnt vmcnt(4)
	v_lshlrev_b64 v[6:7], 12, v[4:5]
	v_lshl_add_u64 v[6:7], v[12:13], 0, v[6:7]
	global_load_dword v3, v[6:7], off
	s_and_b64 vcc, exec, s[4:5]
	s_cbranch_vccnz .LBB0_117
	v_lshl_add_u64 v[4:5], v[4:5], 2, s[12:13]
	global_load_dword v203, v[4:5], off
.LBB0_117:
	v_add_u32_e32 v4, 0x800, v16
	v_ashrrev_i32_e32 v22, 6, v4
	v_add_u32_e32 v6, s3, v22
	v_ashrrev_i32_e32 v7, 31, v6
	v_lshlrev_b64 v[4:5], 12, v[6:7]
	v_lshl_add_u64 v[4:5], v[12:13], 0, v[4:5]
	global_load_dword v4, v[4:5], off
	s_and_b64 vcc, exec, s[4:5]
	s_cbranch_vccnz .LBB0_119
	v_lshl_add_u64 v[6:7], v[6:7], 2, s[12:13]
	global_load_dword v204, v[6:7], off
.LBB0_119:
	v_add_u32_e32 v5, 0xa00, v16
	v_ashrrev_i32_e32 v21, 6, v5
	v_add_u32_e32 v6, s3, v21
	v_ashrrev_i32_e32 v7, 31, v6
	v_lshlrev_b64 v[14:15], 12, v[6:7]
	v_lshl_add_u64 v[14:15], v[12:13], 0, v[14:15]
	global_load_dword v5, v[14:15], off
	s_and_b64 vcc, exec, s[4:5]
	s_cbranch_vccnz .LBB0_121
	v_lshl_add_u64 v[6:7], v[6:7], 2, s[12:13]
	global_load_dword v205, v[6:7], off
.LBB0_121:
	v_add_u32_e32 v6, 0xc00, v16
	v_ashrrev_i32_e32 v20, 6, v6
	v_add_u32_e32 v14, s3, v20
	v_ashrrev_i32_e32 v15, 31, v14
	v_lshlrev_b64 v[6:7], 12, v[14:15]
	v_lshl_add_u64 v[6:7], v[12:13], 0, v[6:7]
	global_load_dword v6, v[6:7], off
	s_and_b64 vcc, exec, s[4:5]
	s_cbranch_vccnz .LBB0_123
	v_lshl_add_u64 v[14:15], v[14:15], 2, s[12:13]
	global_load_dword v206, v[14:15], off
.LBB0_123:
	v_add_u32_e32 v7, 0xe00, v16
	v_ashrrev_i32_e32 v19, 6, v7
	v_add_u32_e32 v14, s3, v19
	v_ashrrev_i32_e32 v15, 31, v14
	v_lshlrev_b64 v[26:27], 12, v[14:15]
	v_lshl_add_u64 v[12:13], v[12:13], 0, v[26:27]
	global_load_dword v7, v[12:13], off
	s_and_b64 vcc, exec, s[4:5]
	s_cbranch_vccnz .LBB0_125
	v_lshl_add_u64 v[12:13], v[14:15], 2, s[12:13]
	global_load_dword v207, v[12:13], off
	s_mov_b32 s100, 1

.LBB0_127:
	s_add_i32 s42, s43, s34
	s_cmpk_gt_i32 s42, 0xff
	s_cselect_b64 s[14:15], -1, 0
	s_and_b64 vcc, exec, s[14:15]
	s_waitcnt vmcnt(0)
	s_cmp_eq_u32 s100, 0
	s_cbranch_scc1 .Lp0nm_1
	v_mul_f32_e32 v0, v0, v200
	v_mul_f32_e32 v1, v1, v201
	v_mul_f32_e32 v2, v2, v202
	v_mul_f32_e32 v3, v3, v203
	v_mul_f32_e32 v4, v4, v204
	v_mul_f32_e32 v5, v5, v205
	v_mul_f32_e32 v6, v6, v206
	v_mul_f32_e32 v7, v7, v207
.Lp0nm_1:
	ds_write_b32 v27, v0
	s_waitcnt vmcnt(6)
	ds_write_b32 v28, v1
	s_waitcnt vmcnt(5)
	ds_write_b32 v29, v2
	s_waitcnt vmcnt(4)
	ds_write_b32 v30, v3
	s_waitcnt vmcnt(3)
	ds_write_b32 v31, v4
	s_waitcnt vmcnt(2)
	ds_write_b32 v32, v5
	s_waitcnt vmcnt(1)
	ds_write_b32 v33, v6
	s_waitcnt vmcnt(0)
	ds_write_b32 v34, v7
	s_waitcnt lgkmcnt(0)
	s_barrier
	s_cbranch_vccnz .LBB0_126
	s_ashr_i32 s48, s42, 31
	s_lshr_b32 s48, s48, 28
	s_add_i32 s48, s42, s48
	s_ashr_i32 s50, s48, 4
	s_lshl_b32 s48, s50, 6
	s_ashr_i32 s49, s48, 31
	v_lshl_add_u64 v[14:15], s[48:49], 2, v[12:13]
	s_lshl_b32 s48, s50, 10
	s_sub_i32 s49, s3, s48
	v_add_u32_e32 v2, s49, v26
	v_ashrrev_i32_e32 v3, 31, v2
	v_lshlrev_b64 v[0:1], 12, v[2:3]
	v_lshl_add_u64 v[0:1], v[14:15], 0, v[0:1]
	s_mov_b32 s100, 0
	global_load_dword v0, v[0:1], off
	s_and_b64 vcc, exec, s[4:5]
	s_cbranch_vccnz .LBB0_130
	v_lshl_add_u64 v[2:3], v[2:3], 2, s[12:13]
	global_load_dword v200, v[2:3], off
.LBB0_130:
	s_sub_i32 s48, 0, s48
	s_add_i32 s48, s48, s3
	v_add_u32_e32 v2, s48, v25
	v_ashrrev_i32_e32 v3, 31, v2
	v_lshlrev_b64 v[4:5], 12, v[2:3]
	v_lshl_add_u64 v[4:5], v[14:15], 0, v[4:5]
	global_load_dword v1, v[4:5], off
	s_and_b64 vcc, exec, s[4:5]
	s_cbranch_vccnz .LBB0_132
	v_lshl_add_u64 v[2:3], v[2:3], 2, s[12:13]
	global_load_dword v201, v[2:3], off
.LBB0_132:
	v_add_u32_e32 v4, s48, v24
	v_ashrrev_i32_e32 v5, 31, v4
	v_lshlrev_b64 v[2:3], 12, v[4:5]
	v_lshl_add_u64 v[2:3], v[14:15], 0, v[2:3]
	global_load_dword v2, v[2:3], off
	s_and_b64 vcc, exec, s[4:5]
	s_cbranch_vccnz .LBB0_134
	v_lshl_add_u64 v[4:5], v[4:5], 2, s[12:13]
	global_load_dword v202, v[4:5], off
.LBB0_134:
	v_add_u32_e32 v4, s48, v23
	v_ashrrev_i32_e32 v5, 31, v4
	v_lshlrev_b64 v[6:7], 12, v[4:5]
	v_lshl_add_u64 v[6:7], v[14:15], 0, v[6:7]
	global_load_dword v3, v[6:7], off
	s_and_b64 vcc, exec, s[4:5]
	s_cbranch_vccnz .LBB0_136
	v_lshl_add_u64 v[4:5], v[4:5], 2, s[12:13]
	global_load_dword v203, v[4:5], off
.LBB0_136:
	v_add_u32_e32 v6, s48, v22
	v_ashrrev_i32_e32 v7, 31, v6
	v_lshlrev_b64 v[4:5], 12, v[6:7]
	v_lshl_add_u64 v[4:5], v[14:15], 0, v[4:5]
	global_load_dword v4, v[4:5], off
	s_and_b64 vcc, exec, s[4:5]
	s_cbranch_vccnz .LBB0_138
	v_lshl_add_u64 v[6:7], v[6:7], 2, s[12:13]
	global_load_dword v204, v[6:7], off
.LBB0_138:
	v_add_u32_e32 v6, s48, v21
	v_ashrrev_i32_e32 v7, 31, v6
	v_lshlrev_b64 v[16:17], 12, v[6:7]
	v_lshl_add_u64 v[16:17], v[14:15], 0, v[16:17]
	global_load_dword v5, v[16:17], off
	s_and_b64 vcc, exec, s[4:5]
	s_cbranch_vccnz .LBB0_140
	v_lshl_add_u64 v[6:7], v[6:7], 2, s[12:13]
	global_load_dword v205, v[6:7], off
.LBB0_140:
	v_add_u32_e32 v16, s48, v20
	v_ashrrev_i32_e32 v17, 31, v16
	v_lshlrev_b64 v[6:7], 12, v[16:17]
	v_lshl_add_u64 v[6:7], v[14:15], 0, v[6:7]
	global_load_dword v6, v[6:7], off
	s_and_b64 vcc, exec, s[4:5]
	s_cbranch_vccnz .LBB0_142
	v_lshl_add_u64 v[16:17], v[16:17], 2, s[12:13]
	global_load_dword v206, v[16:17], off
.LBB0_142:
	v_add_u32_e32 v16, s48, v19
	v_ashrrev_i32_e32 v17, 31, v16
	v_lshlrev_b64 v[36:37], 12, v[16:17]
	v_lshl_add_u64 v[14:15], v[14:15], 0, v[36:37]
	global_load_dword v7, v[14:15], off
	s_and_b64 vcc, exec, s[4:5]
	s_cbranch_vccnz .LBB0_126
	v_lshl_add_u64 v[14:15], v[16:17], 2, s[12:13]
	global_load_dword v207, v[14:15], off
	s_mov_b32 s100, 1
	s_branch .LBB0_126
